# branch phase round-2 tiles as two 128-row half-units on 64 WGs (skip ai=1 MFMAs, gate chunks and stores); conversion slices 2200/2900
# baseline (speedup 1.0000x reference)
.LBB0_100:
	s_andn2_b64 vcc, exec, s[0:1]
	s_cbranch_vccnz .LBB0_149
	s_mov_b32 s100, 0
	s_mov_b32 s101, 0
	s_sub_i32 s0, s84, 32
	s_cmp_lt_u32 s0, 10
	s_cselect_b32 s0, 64, 0x48
	s_lshl_b32 s35, s0, 2
	s_movk_i32 s20, 0x100
	s_waitcnt vmcnt(0)
	v_mov_b32_e32 v0, v193
	s_cmp_lt_i32 s96, s35
	s_mov_b32 s36, s0
	s_cselect_b64 s[0:1], -1, 0
	s_cmp_ge_i32 s96, s35
	v_readfirstlane_b32 s30, v0
	s_cbranch_scc1 .LBB0_103
	s_lshr_b32 s22, s36, 1
	v_readlane_b32 s4, v254, 8
	s_or_b32 s22, s22, s4
	v_readlane_b32 s4, v254, 7
	s_mul_i32 s22, s22, s4
	v_readlane_b32 s4, v254, 4
	s_add_i32 s22, s22, s4
	s_ashr_i32 s23, s22, 31
	s_lshr_b32 s23, s23, 27
	s_add_i32 s23, s22, s23
	s_ashr_i32 s26, s23, 5
	s_lshl_b32 s26, s26, 3
	s_sub_i32 s27, s36, s26
	s_min_i32 s27, s27, 8
	s_sext_i32_i8 s28, s27
	v_cvt_f32_i32_e32 v1, s28
	s_andn2_b32 s23, s23, 31
	s_sub_i32 s29, s22, s23
	v_cvt_f32_i32_e32 v2, s29
	v_rcp_iflag_f32_e32 v3, v1
	s_xor_b32 s22, s29, s28
	s_ashr_i32 s22, s22, 30
	s_or_b32 s28, s22, 1
	v_mul_f32_e32 v3, v2, v3
	v_trunc_f32_e32 v3, v3
	v_fma_f32 v2, -v3, v1, v2
	v_cvt_i32_f32_e32 v3, v3
	v_cmp_ge_f32_e64 s[22:23], |v2|, |v1|
	s_and_b64 s[22:23], s[22:23], exec
	s_cselect_b32 s22, s28, 0
	v_readfirstlane_b32 s23, v3
	s_add_i32 s22, s23, s22
	s_sext_i32_i8 s55, s22
	s_mul_i32 s22, s22, s27
	s_sub_i32 s22, s29, s22
	s_sext_i32_i8 s22, s22
	s_add_i32 s52, s26, s22

.LBB0_107:
	v_cndmask_b32_e64 v206, 1.0, 0, s[36:37]
	v_pk_mul_f32 v[14:15], v[206:207], v[14:15] op_sel_hi:[0,1]
	v_pk_mul_f32 v[12:13], v[206:207], v[12:13] op_sel_hi:[0,1]
	v_pk_mul_f32 v[6:7], v[206:207], v[6:7] op_sel_hi:[0,1]
	v_pk_mul_f32 v[4:5], v[206:207], v[4:5] op_sel_hi:[0,1]
	v_pk_mul_f32 v[22:23], v[206:207], v[22:23] op_sel_hi:[0,1]
	v_pk_mul_f32 v[20:21], v[206:207], v[20:21] op_sel_hi:[0,1]
	v_pk_mul_f32 v[18:19], v[206:207], v[18:19] op_sel_hi:[0,1]
	v_pk_mul_f32 v[16:17], v[206:207], v[16:17] op_sel_hi:[0,1]
	v_pk_mul_f32 v[30:31], v[206:207], v[30:31] op_sel_hi:[0,1]
	v_pk_mul_f32 v[28:29], v[206:207], v[28:29] op_sel_hi:[0,1]
	v_pk_mul_f32 v[26:27], v[206:207], v[26:27] op_sel_hi:[0,1]
	v_pk_mul_f32 v[24:25], v[206:207], v[24:25] op_sel_hi:[0,1]
	v_pk_mul_f32 v[38:39], v[206:207], v[38:39] op_sel_hi:[0,1]
	v_pk_mul_f32 v[36:37], v[206:207], v[36:37] op_sel_hi:[0,1]
	v_pk_mul_f32 v[34:35], v[206:207], v[34:35] op_sel_hi:[0,1]
	v_pk_mul_f32 v[32:33], v[206:207], v[32:33] op_sel_hi:[0,1]
	v_pk_mul_f32 v[46:47], v[206:207], v[46:47] op_sel_hi:[0,1]
	v_pk_mul_f32 v[44:45], v[206:207], v[44:45] op_sel_hi:[0,1]
	v_pk_mul_f32 v[42:43], v[206:207], v[42:43] op_sel_hi:[0,1]
	v_pk_mul_f32 v[40:41], v[206:207], v[40:41] op_sel_hi:[0,1]
	v_pk_mul_f32 v[54:55], v[206:207], v[54:55] op_sel_hi:[0,1]
	v_pk_mul_f32 v[52:53], v[206:207], v[52:53] op_sel_hi:[0,1]
	v_pk_mul_f32 v[50:51], v[206:207], v[50:51] op_sel_hi:[0,1]
	v_pk_mul_f32 v[48:49], v[206:207], v[48:49] op_sel_hi:[0,1]
	v_pk_mul_f32 v[62:63], v[206:207], v[62:63] op_sel_hi:[0,1]
	v_pk_mul_f32 v[60:61], v[206:207], v[60:61] op_sel_hi:[0,1]
	v_pk_mul_f32 v[58:59], v[206:207], v[58:59] op_sel_hi:[0,1]
	v_pk_mul_f32 v[56:57], v[206:207], v[56:57] op_sel_hi:[0,1]
	v_pk_mul_f32 v[70:71], v[206:207], v[102:103] op_sel_hi:[0,1]
	v_pk_mul_f32 v[68:69], v[206:207], v[100:101] op_sel_hi:[0,1]
	v_pk_mul_f32 v[66:67], v[206:207], v[106:107] op_sel_hi:[0,1]
	v_pk_mul_f32 v[64:65], v[206:207], v[104:105] op_sel_hi:[0,1]
	v_pk_mul_f32 v[78:79], v[206:207], v[118:119] op_sel_hi:[0,1]
	v_pk_mul_f32 v[76:77], v[206:207], v[116:117] op_sel_hi:[0,1]
	v_pk_mul_f32 v[74:75], v[206:207], v[122:123] op_sel_hi:[0,1]
	v_pk_mul_f32 v[72:73], v[206:207], v[120:121] op_sel_hi:[0,1]
	v_pk_mul_f32 v[86:87], v[206:207], v[134:135] op_sel_hi:[0,1]
	v_pk_mul_f32 v[84:85], v[206:207], v[132:133] op_sel_hi:[0,1]
	v_pk_mul_f32 v[82:83], v[206:207], v[142:143] op_sel_hi:[0,1]
	v_pk_mul_f32 v[80:81], v[206:207], v[140:141] op_sel_hi:[0,1]
	v_pk_mul_f32 v[94:95], v[206:207], v[154:155] op_sel_hi:[0,1]
	v_pk_mul_f32 v[92:93], v[206:207], v[152:153] op_sel_hi:[0,1]
	v_pk_mul_f32 v[90:91], v[206:207], v[158:159] op_sel_hi:[0,1]
	v_pk_mul_f32 v[88:89], v[206:207], v[156:157] op_sel_hi:[0,1]
	v_pk_mul_f32 v[110:111], v[206:207], v[162:163] op_sel_hi:[0,1]
	v_pk_mul_f32 v[108:109], v[206:207], v[160:161] op_sel_hi:[0,1]
	v_pk_mul_f32 v[98:99], v[206:207], v[166:167] op_sel_hi:[0,1]
	v_pk_mul_f32 v[96:97], v[206:207], v[164:165] op_sel_hi:[0,1]
	v_pk_mul_f32 v[126:127], v[206:207], v[170:171] op_sel_hi:[0,1]
	v_pk_mul_f32 v[124:125], v[206:207], v[168:169] op_sel_hi:[0,1]
	v_pk_mul_f32 v[114:115], v[206:207], v[174:175] op_sel_hi:[0,1]
	v_pk_mul_f32 v[112:113], v[206:207], v[172:173] op_sel_hi:[0,1]
	v_pk_mul_f32 v[138:139], v[206:207], v[178:179] op_sel_hi:[0,1]
	v_pk_mul_f32 v[136:137], v[206:207], v[176:177] op_sel_hi:[0,1]
	v_pk_mul_f32 v[130:131], v[206:207], v[182:183] op_sel_hi:[0,1]
	v_pk_mul_f32 v[128:129], v[206:207], v[180:181] op_sel_hi:[0,1]
	v_pk_mul_f32 v[150:151], v[206:207], v[200:201] op_sel_hi:[0,1]
	v_pk_mul_f32 v[148:149], v[206:207], v[198:199] op_sel_hi:[0,1]
	v_pk_mul_f32 v[146:147], v[206:207], v[204:205] op_sel_hi:[0,1]
	v_pk_mul_f32 v[144:145], v[206:207], v[202:203] op_sel_hi:[0,1]
	v_pk_mul_f32 v[10:11], v[206:207], v[10:11] op_sel_hi:[0,1]
	v_pk_mul_f32 v[8:9], v[206:207], v[8:9] op_sel_hi:[0,1]
	v_pk_mul_f32 v[2:3], v[206:207], v[2:3] op_sel_hi:[0,1]
	v_pk_mul_f32 v[0:1], v[206:207], v[0:1] op_sel_hi:[0,1]
	s_and_b64 vcc, exec, s[46:47]
	s_mov_b32 s100, s101
	s_mov_b32 s26, s43
	s_mov_b32 s55, s42
	s_mov_b32 s52, s44
	s_mov_b64 s[28:29], s[50:51]
	s_mov_b64 s[22:23], s[48:49]
	s_cbranch_vccnz .LBB0_146
.LBB0_108:
	v_readlane_b32 s4, v254, 0
	v_readlane_b32 s5, v254, 1
	s_load_dword s30, s[4:5], 0x0
	s_add_i32 s58, s58, 1
	s_lshr_b32 s27, s58, 2
	s_waitcnt lgkmcnt(0)
	s_mul_i32 s27, s27, s30
	s_add_i32 s27, s27, s96
	s_mov_b32 s101, 0
	s_cmp_gt_u32 s92, 2
	s_cbranch_scc1 .Lbrh_nohalf
	s_lshr_b32 s33, s58, 2
	s_cmp_lg_u32 s33, 1
	s_cbranch_scc1 .Lbrh_nohalf
	s_and_b32 s101, s96, 1
	s_add_i32 s101, s101, 1
	s_lshr_b32 s27, s96, 1
	s_add_i32 s27, s27, 0x100
	s_cmp_lt_u32 s96, 64
	s_cselect_b32 s27, s27, 0x120
.Lbrh_nohalf:
	s_cmp_lt_i32 s27, s35
	s_cselect_b64 s[30:31], -1, 0
	s_cmp_ge_i32 s27, s35
	s_cselect_b64 s[46:47], -1, 0
	s_and_b64 vcc, exec, s[46:47]
	s_cbranch_vccnz .LBB0_110
	s_ashr_i32 s33, s27, 31
	s_lshr_b32 s33, s33, 29
	s_add_i32 s33, s27, s33
	s_ashr_i32 s36, s33, 3
	s_and_b32 s33, s33, -8
	s_sub_i32 s27, s27, s33
	s_lshr_b32 s33, s27, 31
	v_readlane_b32 s4, v255, 49
	s_or_b32 s33, s33, s4
	s_mul_i32 s27, s33, s27
	s_add_i32 s27, s27, s36
	s_ashr_i32 s33, s27, 31
	s_lshr_b32 s33, s33, 27
	s_add_i32 s33, s27, s33
	s_ashr_i32 s36, s33, 5
	s_lshl_b32 s36, s36, 3
	s_sub_i32 s37, s84, s36
	s_min_i32 s37, s37, 8
	s_abs_i32 s38, s37
	v_cvt_f32_u32_e32 v100, s38
	s_sub_i32 s42, 0, s38
	s_andn2_b32 s33, s33, 31
	s_sub_i32 s27, s27, s33
	v_rcp_iflag_f32_e32 v100, v100
	s_abs_i32 s33, s27
	s_xor_b32 s39, s27, s37
	s_ashr_i32 s39, s39, 31
	v_mul_f32_e32 v100, 0x4f7ffffe, v100
	v_cvt_u32_f32_e32 v100, v100
	s_nop 0
	v_readfirstlane_b32 s43, v100
	s_mul_i32 s42, s42, s43
	s_mul_hi_u32 s42, s43, s42
	s_add_i32 s43, s43, s42
	s_mul_hi_u32 s42, s33, s43
	s_mul_i32 s43, s42, s38
	s_sub_i32 s33, s33, s43
	s_add_i32 s44, s42, 1
	s_sub_i32 s43, s33, s38
	s_cmp_ge_u32 s33, s38
	s_cselect_b32 s42, s44, s42
	s_cselect_b32 s33, s43, s33
	s_add_i32 s43, s42, 1
	s_cmp_ge_u32 s33, s38
	s_cselect_b32 s33, s43, s42
	s_xor_b32 s33, s33, s39
	s_sub_i32 s42, s33, s39
	s_mul_i32 s33, s42, s37
	s_sub_i32 s27, s27, s33
	s_add_i32 s44, s27, s36
	s_and_b32 s43, s58, 3
.LBB0_110:
	s_lshl_b32 s36, s43, 8
	s_ashr_i32 s45, s44, 31
	s_ashr_i32 s37, s36, 31
	v_readlane_b32 s4, v253, 16
	s_lshl_b64 s[38:39], s[44:45], 19
	s_lshl_b64 s[36:37], s[36:37], 1
	v_readlane_b32 s8, v253, 20
	v_readlane_b32 s9, v253, 21
	s_add_u32 s27, s8, s38
	s_addc_u32 s33, s9, s39
	s_add_u32 s48, s27, s36
	s_addc_u32 s49, s33, s37
	s_cmp_eq_u32 s101, 2
	s_cselect_b32 s27, 0x40000, 0
	s_add_u32 s48, s48, s27
	s_addc_u32 s49, s49, 0
	s_lshl_b32 s27, s43, 10
	s_lshl_b32 s33, s42, 8
	s_add_i32 s36, s33, s27
	v_readlane_b32 s5, v253, 17
	s_ashr_i32 s37, s36, 31
	s_lshl_b64 s[36:37], s[36:37], 9
	v_readlane_b32 s4, v255, 47
	s_add_u32 s50, s66, s36
	v_readlane_b32 s5, v255, 48
	s_addc_u32 s51, s67, s37
	s_andn2_b64 vcc, exec, s[4:5]
	v_readlane_b32 s6, v253, 18
	v_readlane_b32 s7, v253, 19
	v_readlane_b32 s10, v253, 22
	v_readlane_b32 s11, v253, 23
	v_readlane_b32 s12, v253, 24
	v_readlane_b32 s13, v253, 25
	v_readlane_b32 s14, v253, 26
	v_readlane_b32 s15, v253, 27
	v_readlane_b32 s16, v253, 28
	v_readlane_b32 s17, v253, 29
	v_readlane_b32 s18, v253, 30
	v_readlane_b32 s19, v253, 31
	s_cbranch_vccnz .LBB0_114
	s_and_b64 s[30:31], s[30:31], exec
	s_cselect_b32 s27, s49, s23
	s_cselect_b32 s33, s48, s22
	s_cselect_b32 s36, s51, s29
	s_cselect_b32 s37, s50, s28
	s_add_u32 s22, s22, 0x40080
	s_addc_u32 s23, s23, 0
	s_add_u32 s38, s28, 0x100
	s_mov_b32 s5, s67
	s_mov_b32 s4, s66
	s_addc_u32 s39, s29, 0
	s_mov_b32 s28, 0
.LBB0_112:
	v_or_b32_e32 v100, 0x10000, v244
	v_add_u32_e32 v104, 0x10400, v244
	v_add_u32_e32 v116, 0x10800, v244
	v_add_u32_e32 v120, 0x10c00, v244
	s_add_i32 s45, s28, 2
	ds_read_b128 v[100:103], v100
	ds_read_b128 v[104:107], v104
	ds_read_b128 v[116:119], v116
	ds_read_b128 v[120:123], v120
	s_add_u32 s29, s22, 0xfffc0080
	s_addc_u32 s30, s23, -1
	s_cmp_eq_u32 s68, s28
	s_cselect_b32 s28, s37, s38
	s_cselect_b32 s31, s27, s30
	s_cselect_b32 s30, s33, s29
	s_cselect_b32 s29, s36, s39
	v_lshl_add_u64 v[176:177], s[22:23], 0, v[194:195]
	s_add_i32 m0, s59, 0xc000
	ds_read_b128 v[132:135], v243
	ds_read_b128 v[140:143], v243 offset:1024
	ds_read_b128 v[152:155], v243 offset:2048
	ds_read_b128 v[156:159], v243 offset:3072
	ds_read_b128 v[160:163], v243 offset:4096
	ds_read_b128 v[164:167], v243 offset:5120
	ds_read_b128 v[168:171], v243 offset:6144
	ds_read_b128 v[172:175], v243 offset:7168
	global_load_lds_dwordx4 v[176:177], off
	v_lshl_add_u64 v[176:177], s[22:23], 0, v[196:197]
	s_add_i32 m0, s59, 0xe000
	s_nop 0
	global_load_lds_dwordx4 v[176:177], off
	s_waitcnt lgkmcnt(8)
	s_barrier
	s_waitcnt lgkmcnt(0)
	s_setprio 1
	s_waitcnt lgkmcnt(0)
	v_mfma_f32_16x16x32_bf16 v[148:151], v[100:103], v[132:135], v[148:151]
	v_mfma_f32_16x16x32_bf16 v[144:147], v[116:119], v[132:135], v[144:147]
	v_mfma_f32_16x16x32_bf16 v[136:139], v[100:103], v[152:155], v[136:139]
	v_mfma_f32_16x16x32_bf16 v[128:131], v[116:119], v[152:155], v[128:131]
	v_mfma_f32_16x16x32_bf16 v[124:127], v[100:103], v[160:163], v[124:127]
	v_mfma_f32_16x16x32_bf16 v[112:115], v[116:119], v[160:163], v[112:115]
	v_mfma_f32_16x16x32_bf16 v[108:111], v[100:103], v[168:171], v[108:111]
	v_mfma_f32_16x16x32_bf16 v[96:99], v[116:119], v[168:171], v[96:99]
	v_mfma_f32_16x16x32_bf16 v[148:151], v[104:107], v[140:143], v[148:151]
	v_mfma_f32_16x16x32_bf16 v[144:147], v[120:123], v[140:143], v[144:147]
	v_mfma_f32_16x16x32_bf16 v[136:139], v[104:107], v[156:159], v[136:139]
	v_mfma_f32_16x16x32_bf16 v[128:131], v[120:123], v[156:159], v[128:131]
	v_mfma_f32_16x16x32_bf16 v[124:127], v[104:107], v[164:167], v[124:127]
	v_mfma_f32_16x16x32_bf16 v[112:115], v[120:123], v[164:167], v[112:115]
	v_mfma_f32_16x16x32_bf16 v[108:111], v[104:107], v[172:175], v[108:111]
	v_mfma_f32_16x16x32_bf16 v[96:99], v[120:123], v[172:175], v[96:99]
	s_setprio 0
	s_barrier
	s_mov_b32 m0, s53
	v_or_b32_e32 v176, 0x14000, v244
	v_add_u32_e32 v180, 0x14400, v244
	v_add_u32_e32 v198, 0x14800, v244
	v_add_u32_e32 v202, 0x14c00, v244
	v_lshl_add_u64 v[206:207], s[28:29], 0, v[184:185]
	ds_read_b128 v[176:179], v176
	ds_read_b128 v[180:183], v180
	ds_read_b128 v[198:201], v198
	ds_read_b128 v[202:205], v202
	global_load_lds_dwordx4 v[206:207], off
	v_lshl_add_u64 v[208:209], s[28:29], 0, v[190:191]
	s_mov_b32 m0, s60
	s_nop 0
	global_load_lds_dwordx4 v[208:209], off
	s_barrier
	s_waitcnt lgkmcnt(0)
	s_setprio 1
	s_waitcnt lgkmcnt(0)
	v_mfma_f32_16x16x32_bf16 v[92:95], v[176:179], v[132:135], v[92:95]
	v_mfma_f32_16x16x32_bf16 v[88:91], v[198:201], v[132:135], v[88:91]
	v_mfma_f32_16x16x32_bf16 v[84:87], v[176:179], v[152:155], v[84:87]
	v_mfma_f32_16x16x32_bf16 v[80:83], v[198:201], v[152:155], v[80:83]
	v_mfma_f32_16x16x32_bf16 v[76:79], v[176:179], v[160:163], v[76:79]
	v_mfma_f32_16x16x32_bf16 v[72:75], v[198:201], v[160:163], v[72:75]
	v_mfma_f32_16x16x32_bf16 v[68:71], v[176:179], v[168:171], v[68:71]
	v_mfma_f32_16x16x32_bf16 v[64:67], v[198:201], v[168:171], v[64:67]
	v_mfma_f32_16x16x32_bf16 v[92:95], v[180:183], v[140:143], v[92:95]
	v_mfma_f32_16x16x32_bf16 v[88:91], v[202:205], v[140:143], v[88:91]
	v_mfma_f32_16x16x32_bf16 v[84:87], v[180:183], v[156:159], v[84:87]
	v_mfma_f32_16x16x32_bf16 v[80:83], v[202:205], v[156:159], v[80:83]
	v_mfma_f32_16x16x32_bf16 v[76:79], v[180:183], v[164:167], v[76:79]
	v_mfma_f32_16x16x32_bf16 v[72:75], v[202:205], v[164:167], v[72:75]
	v_mfma_f32_16x16x32_bf16 v[68:71], v[180:183], v[172:175], v[68:71]
	v_mfma_f32_16x16x32_bf16 v[64:67], v[202:205], v[172:175], v[64:67]
	s_setprio 0
	s_mov_b32 m0, s59
	v_lshl_add_u64 v[210:211], s[30:31], 0, v[186:187]
	s_barrier
	ds_read_b128 v[132:135], v243 offset:16384
	ds_read_b128 v[140:143], v243 offset:17408
	ds_read_b128 v[152:155], v243 offset:18432
	ds_read_b128 v[156:159], v243 offset:19456
	ds_read_b128 v[160:163], v243 offset:20480
	ds_read_b128 v[164:167], v243 offset:21504
	ds_read_b128 v[168:171], v243 offset:22528
	ds_read_b128 v[172:175], v243 offset:23552
	global_load_lds_dwordx4 v[210:211], off
	v_lshl_add_u64 v[212:213], s[30:31], 0, v[188:189]
	s_mov_b32 m0, s61
	s_nop 0
	global_load_lds_dwordx4 v[212:213], off
	s_barrier
	s_waitcnt lgkmcnt(0)
	s_setprio 1
	s_waitcnt lgkmcnt(0)
	s_cmp_lg_u32 s100, 0
	s_cbranch_scc1 .Lbrh_s2
	v_mfma_f32_16x16x32_bf16 v[60:63], v[100:103], v[132:135], v[60:63]
	v_mfma_f32_16x16x32_bf16 v[56:59], v[116:119], v[132:135], v[56:59]
	v_mfma_f32_16x16x32_bf16 v[52:55], v[100:103], v[152:155], v[52:55]
	v_mfma_f32_16x16x32_bf16 v[48:51], v[116:119], v[152:155], v[48:51]
	v_mfma_f32_16x16x32_bf16 v[44:47], v[100:103], v[160:163], v[44:47]
	v_mfma_f32_16x16x32_bf16 v[40:43], v[116:119], v[160:163], v[40:43]
	v_mfma_f32_16x16x32_bf16 v[36:39], v[100:103], v[168:171], v[36:39]
	v_mfma_f32_16x16x32_bf16 v[32:35], v[116:119], v[168:171], v[32:35]
	v_mfma_f32_16x16x32_bf16 v[60:63], v[104:107], v[140:143], v[60:63]
	v_mfma_f32_16x16x32_bf16 v[56:59], v[120:123], v[140:143], v[56:59]
	v_mfma_f32_16x16x32_bf16 v[52:55], v[104:107], v[156:159], v[52:55]
	v_mfma_f32_16x16x32_bf16 v[48:51], v[120:123], v[156:159], v[48:51]
	v_mfma_f32_16x16x32_bf16 v[44:47], v[104:107], v[164:167], v[44:47]
	v_mfma_f32_16x16x32_bf16 v[40:43], v[120:123], v[164:167], v[40:43]
	v_mfma_f32_16x16x32_bf16 v[36:39], v[104:107], v[172:175], v[36:39]
	v_mfma_f32_16x16x32_bf16 v[32:35], v[120:123], v[172:175], v[32:35]
.Lbrh_s2:
	s_setprio 0
	s_barrier
	s_add_u32 s66, s28, 0x10000
	s_addc_u32 s67, s29, 0
	s_mov_b32 m0, s62
	v_lshl_add_u64 v[100:101], s[66:67], 0, v[184:185]
	global_load_lds_dwordx4 v[100:101], off
	v_lshl_add_u64 v[100:101], s[66:67], 0, v[190:191]
	s_mov_b32 m0, s63
	s_nop 0
	global_load_lds_dwordx4 v[100:101], off
	s_waitcnt vmcnt(6)
	s_barrier
	s_setprio 1
	s_cmp_lg_u32 s100, 0
	s_cbranch_scc1 .Lbrh_s3
	v_mfma_f32_16x16x32_bf16 v[28:31], v[176:179], v[132:135], v[28:31]
	v_mfma_f32_16x16x32_bf16 v[24:27], v[198:201], v[132:135], v[24:27]
	v_mfma_f32_16x16x32_bf16 v[20:23], v[176:179], v[152:155], v[20:23]
	v_mfma_f32_16x16x32_bf16 v[16:19], v[198:201], v[152:155], v[16:19]
	v_mfma_f32_16x16x32_bf16 v[12:15], v[176:179], v[160:163], v[12:15]
	v_mfma_f32_16x16x32_bf16 v[4:7], v[198:201], v[160:163], v[4:7]
	v_mfma_f32_16x16x32_bf16 v[8:11], v[176:179], v[168:171], v[8:11]
	v_mfma_f32_16x16x32_bf16 v[0:3], v[198:201], v[168:171], v[0:3]
	v_mfma_f32_16x16x32_bf16 v[28:31], v[180:183], v[140:143], v[28:31]
	v_mfma_f32_16x16x32_bf16 v[24:27], v[202:205], v[140:143], v[24:27]
	v_mfma_f32_16x16x32_bf16 v[20:23], v[180:183], v[156:159], v[20:23]
	v_mfma_f32_16x16x32_bf16 v[16:19], v[202:205], v[156:159], v[16:19]
	v_mfma_f32_16x16x32_bf16 v[12:15], v[180:183], v[164:167], v[12:15]
	v_mfma_f32_16x16x32_bf16 v[4:7], v[202:205], v[164:167], v[4:7]
	v_mfma_f32_16x16x32_bf16 v[8:11], v[180:183], v[172:175], v[8:11]
	v_mfma_f32_16x16x32_bf16 v[0:3], v[202:205], v[172:175], v[0:3]
.Lbrh_s3:
	s_setprio 0
	v_or_b32_e32 v100, 0x18000, v244
	v_add_u32_e32 v104, 0x18400, v244
	v_add_u32_e32 v116, 0x18800, v244
	v_add_u32_e32 v120, 0x18c00, v244
	s_barrier
	ds_read_b128 v[100:103], v100
	ds_read_b128 v[104:107], v104
	ds_read_b128 v[116:119], v116
	ds_read_b128 v[120:123], v120
	s_add_u32 s30, s30, 0x40000
	s_addc_u32 s31, s31, 0
	s_mov_b32 m0, s64
	v_lshl_add_u64 v[176:177], s[30:31], 0, v[186:187]
	ds_read_b128 v[132:135], v243 offset:32768
	ds_read_b128 v[140:143], v243 offset:33792
	ds_read_b128 v[152:155], v243 offset:34816
	ds_read_b128 v[156:159], v243 offset:35840
	ds_read_b128 v[160:163], v243 offset:36864
	ds_read_b128 v[164:167], v243 offset:37888
	ds_read_b128 v[168:171], v243 offset:38912
	ds_read_b128 v[172:175], v243 offset:39936
	global_load_lds_dwordx4 v[176:177], off
	v_lshl_add_u64 v[176:177], s[30:31], 0, v[188:189]
	s_mov_b32 m0, s65
	s_nop 0
	global_load_lds_dwordx4 v[176:177], off
	s_waitcnt lgkmcnt(8)
	s_barrier
	s_waitcnt lgkmcnt(0)
	s_setprio 1
	s_waitcnt lgkmcnt(0)
	v_mfma_f32_16x16x32_bf16 v[148:151], v[100:103], v[132:135], v[148:151]
	v_mfma_f32_16x16x32_bf16 v[144:147], v[116:119], v[132:135], v[144:147]
	v_mfma_f32_16x16x32_bf16 v[136:139], v[100:103], v[152:155], v[136:139]
	v_mfma_f32_16x16x32_bf16 v[128:131], v[116:119], v[152:155], v[128:131]
	v_mfma_f32_16x16x32_bf16 v[124:127], v[100:103], v[160:163], v[124:127]
	v_mfma_f32_16x16x32_bf16 v[112:115], v[116:119], v[160:163], v[112:115]
	v_mfma_f32_16x16x32_bf16 v[108:111], v[100:103], v[168:171], v[108:111]
	v_mfma_f32_16x16x32_bf16 v[96:99], v[116:119], v[168:171], v[96:99]
	v_mfma_f32_16x16x32_bf16 v[148:151], v[104:107], v[140:143], v[148:151]
	v_mfma_f32_16x16x32_bf16 v[144:147], v[120:123], v[140:143], v[144:147]
	v_mfma_f32_16x16x32_bf16 v[136:139], v[104:107], v[156:159], v[136:139]
	v_mfma_f32_16x16x32_bf16 v[128:131], v[120:123], v[156:159], v[128:131]
	v_mfma_f32_16x16x32_bf16 v[124:127], v[104:107], v[164:167], v[124:127]
	v_mfma_f32_16x16x32_bf16 v[112:115], v[120:123], v[164:167], v[112:115]
	v_mfma_f32_16x16x32_bf16 v[108:111], v[104:107], v[172:175], v[108:111]
	v_mfma_f32_16x16x32_bf16 v[96:99], v[120:123], v[172:175], v[96:99]
	s_setprio 0
	s_barrier
	s_mov_b32 m0, s69
	v_or_b32_e32 v176, 0x1c000, v244
	v_add_u32_e32 v180, 0x1c400, v244
	v_add_u32_e32 v198, 0x1c800, v244
	v_add_u32_e32 v202, 0x1cc00, v244
	v_lshl_add_u64 v[206:207], v[206:207], 0, s[24:25]
	ds_read_b128 v[176:179], v176
	ds_read_b128 v[180:183], v180
	ds_read_b128 v[198:201], v198
	ds_read_b128 v[202:205], v202
	global_load_lds_dwordx4 v[206:207], off
	v_lshl_add_u64 v[206:207], v[208:209], 0, s[24:25]
	s_mov_b32 m0, s70
	s_nop 0
	global_load_lds_dwordx4 v[206:207], off
	s_barrier
	s_waitcnt lgkmcnt(0)
	s_setprio 1
	s_waitcnt lgkmcnt(0)
	v_mfma_f32_16x16x32_bf16 v[92:95], v[176:179], v[132:135], v[92:95]
	v_mfma_f32_16x16x32_bf16 v[88:91], v[198:201], v[132:135], v[88:91]
	v_mfma_f32_16x16x32_bf16 v[84:87], v[176:179], v[152:155], v[84:87]
	v_mfma_f32_16x16x32_bf16 v[80:83], v[198:201], v[152:155], v[80:83]
	v_mfma_f32_16x16x32_bf16 v[76:79], v[176:179], v[160:163], v[76:79]
	v_mfma_f32_16x16x32_bf16 v[72:75], v[198:201], v[160:163], v[72:75]
	v_mfma_f32_16x16x32_bf16 v[68:71], v[176:179], v[168:171], v[68:71]
	v_mfma_f32_16x16x32_bf16 v[64:67], v[198:201], v[168:171], v[64:67]
	v_mfma_f32_16x16x32_bf16 v[92:95], v[180:183], v[140:143], v[92:95]
	v_mfma_f32_16x16x32_bf16 v[88:91], v[202:205], v[140:143], v[88:91]
	v_mfma_f32_16x16x32_bf16 v[84:87], v[180:183], v[156:159], v[84:87]
	v_mfma_f32_16x16x32_bf16 v[80:83], v[202:205], v[156:159], v[80:83]
	v_mfma_f32_16x16x32_bf16 v[76:79], v[180:183], v[164:167], v[76:79]
	v_mfma_f32_16x16x32_bf16 v[72:75], v[202:205], v[164:167], v[72:75]
	v_mfma_f32_16x16x32_bf16 v[68:71], v[180:183], v[172:175], v[68:71]
	v_mfma_f32_16x16x32_bf16 v[64:67], v[202:205], v[172:175], v[64:67]
	s_setprio 0
	s_mov_b32 m0, s71
	v_lshl_add_u64 v[206:207], v[210:211], 0, s[24:25]
	s_barrier
	ds_read_b128 v[132:135], v243 offset:49152
	ds_read_b128 v[140:143], v243 offset:50176
	ds_read_b128 v[152:155], v243 offset:51200
	ds_read_b128 v[156:159], v243 offset:52224
	ds_read_b128 v[160:163], v243 offset:53248
	ds_read_b128 v[164:167], v243 offset:54272
	ds_read_b128 v[168:171], v243 offset:55296
	ds_read_b128 v[172:175], v243 offset:56320
	global_load_lds_dwordx4 v[206:207], off
	v_lshl_add_u64 v[206:207], v[212:213], 0, s[24:25]
	s_mov_b32 m0, s54
	s_nop 0
	global_load_lds_dwordx4 v[206:207], off
	s_barrier
	s_waitcnt lgkmcnt(0)
	s_setprio 1
	s_waitcnt lgkmcnt(0)
	s_cmp_lg_u32 s100, 0
	s_cbranch_scc1 .Lbrh_s6
	v_mfma_f32_16x16x32_bf16 v[60:63], v[100:103], v[132:135], v[60:63]
	v_mfma_f32_16x16x32_bf16 v[56:59], v[116:119], v[132:135], v[56:59]
	v_mfma_f32_16x16x32_bf16 v[52:55], v[100:103], v[152:155], v[52:55]
	v_mfma_f32_16x16x32_bf16 v[48:51], v[116:119], v[152:155], v[48:51]
	v_mfma_f32_16x16x32_bf16 v[44:47], v[100:103], v[160:163], v[44:47]
	v_mfma_f32_16x16x32_bf16 v[40:43], v[116:119], v[160:163], v[40:43]
	v_mfma_f32_16x16x32_bf16 v[36:39], v[100:103], v[168:171], v[36:39]
	v_mfma_f32_16x16x32_bf16 v[32:35], v[116:119], v[168:171], v[32:35]
	v_mfma_f32_16x16x32_bf16 v[60:63], v[104:107], v[140:143], v[60:63]
	v_mfma_f32_16x16x32_bf16 v[56:59], v[120:123], v[140:143], v[56:59]
	v_mfma_f32_16x16x32_bf16 v[52:55], v[104:107], v[156:159], v[52:55]
	v_mfma_f32_16x16x32_bf16 v[48:51], v[120:123], v[156:159], v[48:51]
	v_mfma_f32_16x16x32_bf16 v[44:47], v[104:107], v[164:167], v[44:47]
	v_mfma_f32_16x16x32_bf16 v[40:43], v[120:123], v[164:167], v[40:43]
	v_mfma_f32_16x16x32_bf16 v[36:39], v[104:107], v[172:175], v[36:39]
	v_mfma_f32_16x16x32_bf16 v[32:35], v[120:123], v[172:175], v[32:35]
.Lbrh_s6:
	s_setprio 0
	s_barrier
	s_add_u32 s28, s28, 0x10080
	s_addc_u32 s29, s29, 0
	s_mov_b32 m0, s40
	v_lshl_add_u64 v[100:101], s[28:29], 0, v[184:185]
	global_load_lds_dwordx4 v[100:101], off
	v_lshl_add_u64 v[100:101], s[28:29], 0, v[190:191]
	s_mov_b32 m0, s41
	s_nop 0
	global_load_lds_dwordx4 v[100:101], off
	s_waitcnt vmcnt(6)
	s_barrier
	s_setprio 1
	s_cmp_lg_u32 s100, 0
	s_cbranch_scc1 .Lbrh_s7
	v_mfma_f32_16x16x32_bf16 v[28:31], v[176:179], v[132:135], v[28:31]
	v_mfma_f32_16x16x32_bf16 v[24:27], v[198:201], v[132:135], v[24:27]
	v_mfma_f32_16x16x32_bf16 v[20:23], v[176:179], v[152:155], v[20:23]
	v_mfma_f32_16x16x32_bf16 v[16:19], v[198:201], v[152:155], v[16:19]
	v_mfma_f32_16x16x32_bf16 v[12:15], v[176:179], v[160:163], v[12:15]
	v_mfma_f32_16x16x32_bf16 v[4:7], v[198:201], v[160:163], v[4:7]
	v_mfma_f32_16x16x32_bf16 v[8:11], v[176:179], v[168:171], v[8:11]
	v_mfma_f32_16x16x32_bf16 v[0:3], v[198:201], v[168:171], v[0:3]
	v_mfma_f32_16x16x32_bf16 v[28:31], v[180:183], v[140:143], v[28:31]
	v_mfma_f32_16x16x32_bf16 v[24:27], v[202:205], v[140:143], v[24:27]
	v_mfma_f32_16x16x32_bf16 v[20:23], v[180:183], v[156:159], v[20:23]
	v_mfma_f32_16x16x32_bf16 v[16:19], v[202:205], v[156:159], v[16:19]
	v_mfma_f32_16x16x32_bf16 v[12:15], v[180:183], v[164:167], v[12:15]
	v_mfma_f32_16x16x32_bf16 v[4:7], v[202:205], v[164:167], v[4:7]
	v_mfma_f32_16x16x32_bf16 v[8:11], v[180:183], v[172:175], v[8:11]
	v_mfma_f32_16x16x32_bf16 v[0:3], v[202:205], v[172:175], v[0:3]
.Lbrh_s7:
	s_setprio 0
	s_add_u32 s22, s22, 0x100
	s_addc_u32 s23, s23, 0
	s_add_u32 s38, s38, 0x100
	s_addc_u32 s39, s39, 0
	s_cmp_ge_i32 s45, s34
	s_mov_b32 s28, s45
	s_barrier
	s_cbranch_scc0 .LBB0_112
	s_mov_b32 s66, s4
	s_mov_b32 s67, s5
.LBB0_114:
	s_cmp_eq_u32 s100, 2
	s_cbranch_scc0 .Lbrh_nsh
	v_add_u32_e32 v242, 0x80, v242
	v_add_u32_e32 v246, 0x80, v246
.Lbrh_nsh:
	s_lshl_b32 s22, s52, 4
	s_lshl_b32 s28, s26, 5
	s_add_i32 s22, s22, s20
	s_cmp_eq_u32 s100, 2
	s_cselect_b32 s27, 8, 0
	s_add_i32 s22, s22, s27
	s_ashr_i32 s29, s28, 31
	s_lshl_b32 s27, s55, 3
	s_ashr_i32 s23, s22, 31
	s_ashr_i32 s30, s27, 31
	s_or_b64 s[28:29], s[28:29], s[0:1]
	s_add_u32 s28, s28, s27
	s_addc_u32 s29, s29, s30
	s_lshl_b64 s[22:23], s[22:23], 17
	s_lshl_b64 s[28:29], s[28:29], 10
	s_add_u32 s22, s78, s22
	s_addc_u32 s23, s79, s23
	s_add_u32 s22, s22, s28
	s_addc_u32 s23, s23, s29
	v_mov_b32_e32 v100, v245
	s_cmp_eq_u32 s26, 3
	s_cselect_b64 s[36:37], -1, 0
	v_ashrrev_i32_e32 v101, 31, v100
	v_lshl_add_u64 v[208:209], v[100:101], 4, s[22:23]
	s_and_b64 s[28:29], s[36:37], exec
	global_load_dwordx4 v[198:201], v[208:209], off
	s_cselect_b32 s27, 0, 0x800
	s_lshl_b32 s88, s27, 4
	v_lshl_add_u64 v[100:101], v[208:209], 0, s[88:89]
	global_load_dwordx4 v[202:205], v[100:101], off
	s_mov_b64 s[22:23], 0x20000
	v_lshl_add_u64 v[100:101], v[208:209], 0, s[22:23]
	s_mov_b32 s22, 0x21000
	v_add_co_u32_e32 v102, vcc, s22, v208
	v_lshl_add_u64 v[100:101], v[100:101], 0, s[88:89]
	s_nop 0
	v_addc_co_u32_e32 v103, vcc, 0, v209, vcc
	s_mov_b64 s[22:23], 0x40000
	global_load_dwordx4 v[180:183], v[102:103], off offset:-4096
	global_load_dwordx4 v[176:179], v[100:101], off
	v_lshl_add_u64 v[100:101], v[208:209], 0, s[22:23]
	s_mov_b32 s22, 0x41000
	v_lshl_add_u64 v[100:101], v[100:101], 0, s[88:89]
	v_add_co_u32_e32 v104, vcc, s22, v208
	global_load_dwordx4 v[172:175], v[100:101], off
	global_load_dwordx4 v[140:143], v[102:103], off
	v_lshl_add_u64 v[100:101], v[208:209], 0, s[82:83]
	v_addc_co_u32_e32 v105, vcc, 0, v209, vcc
	v_lshl_add_u64 v[100:101], v[100:101], 0, s[88:89]
	global_load_dwordx4 v[168:171], v[104:105], off offset:-4096
	global_load_dwordx4 v[160:163], v[100:101], off
	s_mov_b32 s22, 0x61000
	v_lshl_add_u64 v[100:101], v[208:209], 0, s[94:95]
	v_add_co_u32_e32 v106, vcc, s22, v208
	v_lshl_add_u64 v[100:101], v[100:101], 0, s[88:89]
	s_mov_b64 s[22:23], 0x21000
	global_load_dwordx4 v[152:155], v[100:101], off
	global_load_dwordx4 v[120:123], v[104:105], off
	v_lshl_add_u64 v[100:101], v[208:209], 0, s[22:23]
	v_addc_co_u32_e32 v107, vcc, 0, v209, vcc
	s_movk_i32 s4, 0x1000
	v_lshl_add_u64 v[100:101], v[100:101], 0, s[88:89]
	s_mov_b64 s[22:23], 0x41000
	global_load_dwordx4 v[164:167], v[106:107], off offset:-4096
	global_load_dwordx4 v[132:135], v[100:101], off
	v_add_co_u32_e32 v116, vcc, s4, v208
	v_lshl_add_u64 v[100:101], v[208:209], 0, s[22:23]
	s_nop 0
	v_addc_co_u32_e32 v117, vcc, 0, v209, vcc
	v_lshl_add_u64 v[100:101], v[100:101], 0, s[88:89]
	s_mov_b64 s[22:23], 0x61000
	global_load_dwordx4 v[156:159], v[116:117], off
	s_movk_i32 s33, 0x3fff
	global_load_dwordx4 v[116:119], v[100:101], off
	s_cmp_lg_u32 s26, 3
	global_load_dwordx4 v[104:107], v[106:107], off
	v_lshl_add_u64 v[100:101], v[208:209], 0, s[22:23]
	v_lshl_add_u64 v[100:101], v[100:101], 0, s[88:89]
	global_load_dwordx4 v[100:103], v[100:101], off
	v_lshl_add_u32 v216, s52, 8, v242
	s_waitcnt vmcnt(14)
	v_lshlrev_b32_e32 v206, 16, v198
	v_and_b32_e32 v207, 0xffff0000, v198
	v_rcp_f32_e32 v206, v206
	v_rcp_f32_e32 v207, v207
	v_lshlrev_b32_e32 v210, 16, v199
	v_and_b32_e32 v211, 0xffff0000, v199
	v_lshlrev_b32_e32 v198, 16, v202
	v_and_b32_e32 v199, 0xffff0000, v202
	v_pk_mul_f32 v[198:199], v[206:207], v[198:199]
	v_lshlrev_b32_e32 v212, 16, v200
	v_cndmask_b32_e64 v199, v199, v207, s[36:37]
	v_cndmask_b32_e64 v198, v198, v206, s[36:37]
	v_pk_mul_f32 v[198:199], v[148:149], v[198:199]
	v_rcp_f32_e32 v148, v210
	v_rcp_f32_e32 v149, v211
	v_and_b32_e32 v213, 0xffff0000, v200
	v_lshlrev_b32_e32 v214, 16, v201
	v_and_b32_e32 v215, 0xffff0000, v201
	v_lshlrev_b32_e32 v200, 16, v203
	v_and_b32_e32 v201, 0xffff0000, v203
	v_pk_mul_f32 v[200:201], v[148:149], v[200:201]
	v_lshlrev_b32_e32 v202, 16, v204
	v_cndmask_b32_e64 v149, v201, v149, s[36:37]
	v_cndmask_b32_e64 v148, v200, v148, s[36:37]
	v_pk_mul_f32 v[200:201], v[150:151], v[148:149]
	v_rcp_f32_e32 v148, v212
	v_rcp_f32_e32 v149, v213
	v_and_b32_e32 v203, 0xffff0000, v204
	v_lshlrev_b32_e32 v204, 16, v205
	v_and_b32_e32 v205, 0xffff0000, v205
	v_pk_mul_f32 v[150:151], v[148:149], v[202:203]
	v_lshl_or_b32 v206, s55, 8, v192
	v_cndmask_b32_e64 v149, v151, v149, s[36:37]
	v_cndmask_b32_e64 v148, v150, v148, s[36:37]
	v_pk_mul_f32 v[202:203], v[144:145], v[148:149]
	v_rcp_f32_e32 v144, v214
	v_rcp_f32_e32 v145, v215
	s_nop 0
	v_pk_mul_f32 v[148:149], v[144:145], v[204:205]
	s_nop 0
	v_cndmask_b32_e64 v145, v149, v145, s[36:37]
	v_cndmask_b32_e64 v144, v148, v144, s[36:37]
	v_pk_mul_f32 v[204:205], v[146:147], v[144:145]
	s_cbranch_scc1 .LBB0_116
	v_ashrrev_i32_e32 v217, 31, v216
	v_readlane_b32 s4, v253, 16
	v_lshlrev_b64 v[148:149], 11, v[216:217]
	v_readlane_b32 s6, v253, 18
	v_readlane_b32 s7, v253, 19
	v_ashrrev_i32_e32 v207, 31, v206
	v_cvt_pk_bf16_f32 v144, v198, v199
	v_cvt_pk_bf16_f32 v145, v200, v201
	v_cvt_pk_bf16_f32 v146, v202, v203
	v_cvt_pk_bf16_f32 v147, v204, v205
	s_nop 0
	v_lshl_add_u64 v[148:149], s[6:7], 0, v[148:149]
	v_lshl_add_u64 v[148:149], v[206:207], 1, v[148:149]
	v_readlane_b32 s5, v253, 17
	v_readlane_b32 s8, v253, 20
	v_readlane_b32 s9, v253, 21
	v_readlane_b32 s10, v253, 22
	v_readlane_b32 s11, v253, 23
	v_readlane_b32 s12, v253, 24
	v_readlane_b32 s13, v253, 25
	v_readlane_b32 s14, v253, 26
	v_readlane_b32 s15, v253, 27
	v_readlane_b32 s16, v253, 28
	v_readlane_b32 s17, v253, 29
	v_readlane_b32 s18, v253, 30
	v_readlane_b32 s19, v253, 31
	global_store_dwordx4 v[148:149], v[144:147], off

.LBB0_130:
	s_cmp_lg_u32 s100, 0
	s_cbranch_scc1 .Lbrh_skip
	s_mov_b64 s[22:23], 0x101000
	s_nop 0
	v_lshl_add_u64 v[64:65], v[208:209], 0, s[22:23]
	v_add_co_u32_e32 v66, vcc, 0x101000, v208
	v_lshl_add_u64 v[64:65], v[64:65], 0, s[88:89]
	s_nop 0
	v_addc_co_u32_e32 v67, vcc, 0, v209, vcc
	s_mov_b64 s[22:23], 0x121000
	global_load_dwordx4 v[88:91], v[66:67], off
	global_load_dwordx4 v[92:95], v[64:65], off
	v_lshl_add_u64 v[64:65], v[208:209], 0, s[22:23]
	v_add_co_u32_e32 v66, vcc, 0x121000, v208
	v_lshl_add_u64 v[64:65], v[64:65], 0, s[88:89]
	s_nop 0
	v_addc_co_u32_e32 v67, vcc, 0, v209, vcc
	s_mov_b64 s[22:23], 0x141000
	global_load_dwordx4 v[80:83], v[66:67], off
	global_load_dwordx4 v[84:87], v[64:65], off
	v_lshl_add_u64 v[64:65], v[208:209], 0, s[22:23]
	v_add_co_u32_e32 v66, vcc, 0x141000, v208
	v_lshl_add_u64 v[64:65], v[64:65], 0, s[88:89]
	s_nop 0
	v_addc_co_u32_e32 v67, vcc, 0, v209, vcc
	s_mov_b64 s[22:23], 0x161000
	global_load_dwordx4 v[72:75], v[66:67], off
	global_load_dwordx4 v[76:79], v[64:65], off
	v_lshl_add_u64 v[68:69], v[208:209], 0, s[22:23]
	v_add_co_u32_e32 v64, vcc, 0x161000, v208
	v_lshl_add_u64 v[68:69], v[68:69], 0, s[88:89]
	s_nop 0
	v_addc_co_u32_e32 v65, vcc, 0, v209, vcc
	global_load_dwordx4 v[64:67], v[64:65], off
	s_waitcnt vmcnt(13)
	v_lshlrev_b32_e32 v207, 16, v144
	global_load_dwordx4 v[68:71], v[68:69], off
	v_and_b32_e32 v209, 0xffff0000, v144
	v_rcp_f32_e32 v208, v207
	v_rcp_f32_e32 v209, v209
	v_lshlrev_b32_e32 v210, 16, v145
	v_and_b32_e32 v211, 0xffff0000, v145
	v_lshlrev_b32_e32 v144, 16, v148
	v_and_b32_e32 v145, 0xffff0000, v148
	v_pk_mul_f32 v[144:145], v[208:209], v[144:145]
	v_lshlrev_b32_e32 v212, 16, v146
	v_cndmask_b32_e64 v145, v145, v209, s[36:37]
	v_cndmask_b32_e64 v144, v144, v208, s[36:37]
	v_pk_mul_f32 v[60:61], v[60:61], v[144:145]
	v_rcp_f32_e32 v144, v210
	v_rcp_f32_e32 v145, v211
	v_and_b32_e32 v213, 0xffff0000, v146
	v_lshlrev_b32_e32 v214, 16, v147
	v_and_b32_e32 v215, 0xffff0000, v147
	v_lshlrev_b32_e32 v146, 16, v149
	v_and_b32_e32 v147, 0xffff0000, v149
	v_pk_mul_f32 v[146:147], v[144:145], v[146:147]
	v_lshlrev_b32_e32 v148, 16, v150
	v_cndmask_b32_e64 v145, v147, v145, s[36:37]
	v_cndmask_b32_e64 v144, v146, v144, s[36:37]
	v_pk_mul_f32 v[62:63], v[62:63], v[144:145]
	v_rcp_f32_e32 v144, v212
	v_rcp_f32_e32 v145, v213
	v_and_b32_e32 v149, 0xffff0000, v150
	v_lshlrev_b32_e32 v150, 16, v151
	v_and_b32_e32 v151, 0xffff0000, v151
	v_pk_mul_f32 v[146:147], v[144:145], v[148:149]
	s_and_b64 vcc, exec, s[38:39]
	v_cndmask_b32_e64 v145, v147, v145, s[36:37]
	v_cndmask_b32_e64 v144, v146, v144, s[36:37]
	v_pk_mul_f32 v[56:57], v[56:57], v[144:145]
	v_rcp_f32_e32 v144, v214
	v_rcp_f32_e32 v145, v215
	s_nop 0
	v_pk_mul_f32 v[146:147], v[144:145], v[150:151]
	s_nop 0
	v_cndmask_b32_e64 v145, v147, v145, s[36:37]
	v_cndmask_b32_e64 v144, v146, v144, s[36:37]
	v_pk_mul_f32 v[58:59], v[58:59], v[144:145]
	v_lshl_add_u32 v144, s52, 8, v247
	s_cbranch_vccnz .LBB0_132
	v_ashrrev_i32_e32 v145, 31, v144
	v_readlane_b32 s4, v253, 16
	v_lshlrev_b64 v[150:151], 11, v[144:145]
	v_readlane_b32 s6, v253, 18
	v_readlane_b32 s7, v253, 19
	v_ashrrev_i32_e32 v207, 31, v206
	v_cvt_pk_bf16_f32 v146, v60, v61
	v_cvt_pk_bf16_f32 v147, v62, v63
	v_cvt_pk_bf16_f32 v148, v56, v57
	v_cvt_pk_bf16_f32 v149, v58, v59
	s_nop 0
	v_lshl_add_u64 v[150:151], s[6:7], 0, v[150:151]
	v_lshl_add_u64 v[150:151], v[206:207], 1, v[150:151]
	v_readlane_b32 s5, v253, 17
	v_readlane_b32 s8, v253, 20
	v_readlane_b32 s9, v253, 21
	v_readlane_b32 s10, v253, 22
	v_readlane_b32 s11, v253, 23
	v_readlane_b32 s12, v253, 24
	v_readlane_b32 s13, v253, 25
	v_readlane_b32 s14, v253, 26
	v_readlane_b32 s15, v253, 27
	v_readlane_b32 s16, v253, 28
	v_readlane_b32 s17, v253, 29
	v_readlane_b32 s18, v253, 30
	v_readlane_b32 s19, v253, 31
	global_store_dwordx4 v[150:151], v[146:149], off

.Lbrh_skip:
	s_waitcnt vmcnt(0)
	s_cmp_eq_u32 s100, 2
	s_cbranch_scc0 .LBB0_107
	v_add_u32_e32 v242, 0xffffff80, v242
	v_add_u32_e32 v246, 0xffffff80, v246
	s_branch .LBB0_107

.LBB0_149:
	s_cmp_gt_i32 s84, 31
	v_readlane_b32 s4, v254, 9
	s_cselect_b64 s[0:1], -1, 0
	v_readlane_b32 s5, v254, 10
	s_or_b64 s[0:1], s[0:1], s[4:5]
	s_and_b64 vcc, exec, s[0:1]
	s_cbranch_vccnz .LBB0_187
	s_cmp_eq_u32 s91, 5
	s_movk_i32 s0, 0x898
	s_cselect_b32 s20, s0, 0xb54
	s_movk_i32 s0, 0x1080
	v_readfirstlane_b32 s22, v193
	s_cselect_b32 s23, 0xb54, s0
	s_and_b64 s[0:1], s[56:57], exec
	s_cselect_b32 s26, 0, s20
	s_lshr_b32 s22, s22, 8
	s_and_b64 s[0:1], s[56:57], exec
	v_readlane_b32 s0, v254, 12
	s_cselect_b32 s20, 0x898, s23
	s_add_i32 s0, s0, s26
	s_add_i32 s50, s0, s22
	s_waitcnt vmcnt(0)
	v_mov_b32_e32 v1, v218
	s_cmp_ge_i32 s50, s20
	s_waitcnt vmcnt(0) lgkmcnt(0)
	s_barrier
	s_cbranch_scc1 .LBB0_187
	v_readlane_b32 s0, v254, 0
	v_readlane_b32 s1, v254, 1
	s_load_dword s0, s[0:1], 0x0
	s_add_i32 s28, s92, 1
	v_readlane_b32 s52, v253, 0
	v_readlane_b32 s54, v253, 2
	v_readlane_b32 s55, v253, 3
	s_waitcnt lgkmcnt(0)
	s_lshl_b32 s0, s0, 1
	s_sub_i32 s51, s0, 0x80
	s_bitcmp1_b32 s28, 0
	s_cselect_b32 s0, 0x2180000, 0
	s_add_u32 s38, s54, s0
	v_readlane_b32 s56, v253, 4
	s_addc_u32 s39, s55, 0
	v_readlane_b32 s57, v253, 5
	s_add_u32 s40, s56, s0
	v_readlane_b32 s58, v253, 6
	s_addc_u32 s41, s57, 0
	v_cvt_f32_i32_e32 v7, v1
	v_readlane_b32 s59, v253, 7
	s_add_u32 s42, s58, s0
	v_readlane_b32 s60, v253, 8
	s_addc_u32 s43, s59, 0
	v_readlane_b32 s61, v253, 9
	s_add_u32 s44, s60, s0
	v_readlane_b32 s62, v253, 10
	s_addc_u32 s45, s61, 0
	v_mul_f32_e32 v7, 0x3d000000, v7
	v_readlane_b32 s63, v253, 11
	s_add_u32 s46, s62, s0
	v_readlane_b32 s4, v253, 32
	v_mul_f32_e64 v8, |v7|, 0.5
	s_mul_i32 s22, s28, 0x1900000
	s_addc_u32 s47, s63, 0
	s_ashr_i32 s29, s28, 31
	v_readlane_b32 s18, v253, 46
	v_fract_f32_e32 v9, v8
	s_mul_hi_i32 s1, s28, 0x1900000
	v_readlane_b32 s19, v253, 47
	s_add_u32 s48, s18, s22
	v_add_f32_e32 v9, v9, v9
	v_cmp_neq_f32_e32 vcc, s21, v8
	s_addc_u32 s49, s19, s1
	v_cmp_gt_f32_e64 s[0:1], |v7|, 1.0
	v_cndmask_b32_e32 v8, 0, v9, vcc
	v_readlane_b32 s53, v253, 1
	v_cndmask_b32_e64 v8, |v7|, v8, s[0:1]
	v_add_f32_e32 v9, v8, v8
	v_rndne_f32_e32 v9, v9
	v_fmac_f32_e32 v8, -0.5, v9
	v_mul_f32_e32 v11, v8, v8
	v_fmamk_f32 v12, v11, 0x3e75aa41, v220
	v_fmaak_f32 v12, v11, v12, 0x40234736
	v_fmaak_f32 v12, v11, v12, 0xc0a55e0e
	v_mul_f32_e32 v13, v8, v11
	v_mul_f32_e32 v12, v13, v12
	v_cvt_i32_f32_e32 v10, v9
	v_fmac_f32_e32 v12, 0x40490fdb, v8
	v_fmamk_f32 v8, v11, 0x3d4be544, v221
	v_fmaak_f32 v8, v11, v8, 0xbfaad1da
	v_fmaak_f32 v8, v11, v8, 0x4081e0d3
	v_fmaak_f32 v8, v11, v8, 0xc09de9e6
	v_fma_f32 v8, v11, v8, 1.0
	v_and_b32_e32 v11, 1, v10
	v_readlane_b32 s64, v253, 12
	v_readlane_b32 s65, v253, 13
	v_readlane_b32 s66, v253, 14
	v_readlane_b32 s67, v253, 15
	v_lshlrev_b32_e32 v6, 2, v1
	v_cmp_eq_u32_e32 vcc, 0, v11
	v_readlane_b32 s52, v253, 48
	v_ashrrev_i32_e32 v0, 4, v1
	v_and_b32_e32 v2, 60, v6
	v_and_b32_e32 v34, 63, v1
	v_ashrrev_i32_e32 v35, 2, v1
	v_cmp_gt_i32_e64 s[36:37], 64, v1
	v_and_b32_e32 v1, 0x7fffffff, v7
	v_and_b32_e32 v9, 2, v10
	v_cndmask_b32_e64 v11, -v12, v8, vcc
	v_add_u32_e32 v39, s2, v6
	v_cndmask_b32_e32 v6, v8, v12, vcc
	v_lshlrev_b32_e32 v8, 30, v10
	s_lshl_b64 s[22:23], s[28:29], 22
	v_readlane_b32 s60, v253, 56
	v_cmp_eq_u32_e64 s[0:1], 0, v9
	v_and_b32_e32 v8, 0x80000000, v8
	v_xor_b32_e32 v1, v1, v7
	v_readlane_b32 s53, v253, 49
	v_readlane_b32 s61, v253, 57
	s_add_u32 s52, s60, s22
	v_cndmask_b32_e64 v9, -v11, v11, s[0:1]
	s_movk_i32 s0, 0x1f8
	v_xor_b32_e32 v1, v1, v8
	s_addc_u32 s53, s61, s23
	s_lshl_b64 s[34:35], s[28:29], 16
	s_lshl_b64 s[30:31], s[28:29], 10
	v_cmp_class_f32_e64 s[0:1], v7, s0
	v_xor_b32_e32 v1, v1, v6
	v_readlane_b32 s54, v253, 50
	s_add_u32 s29, s52, 0x300000
	v_and_b32_e32 v3, -16, v35
	v_cndmask_b32_e64 v38, v236, v9, s[0:1]
	v_cndmask_b32_e64 v40, v236, v1, s[0:1]
	s_movk_i32 s0, 0x41
	v_readlane_b32 s56, v253, 52
	s_addc_u32 s54, s53, 0
	v_mad_u64_u32 v[10:11], s[0:1], v0, s0, v[2:3]
	v_readlane_b32 s57, v253, 53
	s_add_u32 s0, s56, s34
	v_readlane_b32 s58, v253, 54
	s_addc_u32 s1, s57, s35
	v_readlane_b32 s55, v253, 51
	v_readlane_b32 s59, v253, 55
	s_add_u32 s26, s58, s30
	v_readlane_b32 s66, v253, 62
	s_mul_i32 s55, s28, 0xb00000
	s_addc_u32 s27, s59, s31
	v_readlane_b32 s67, v253, 63
	s_mul_hi_i32 s33, s28, 0xb00000
	s_mul_hi_i32 s60, s28, 0x1600000
	s_mul_i32 s61, s28, 0x1600000
	s_add_u32 s28, s66, s55
	v_readlane_b32 s64, v253, 60
	s_addc_u32 s30, s67, s33
	v_readlane_b32 s65, v253, 61
	s_add_u32 s31, s64, s61
	v_readlane_b32 s62, v253, 58
	v_lshlrev_b32_e32 v184, 1, v34
	v_mov_b32_e32 v36, s2
	v_ashrrev_i32_e32 v1, 31, v0
	v_add_u32_e32 v12, 16, v0
	s_addc_u32 s34, s65, s60
	v_readlane_b32 s63, v253, 59
	v_lshl_add_u64 v[4:5], s[40:41], 0, v[184:185]
	v_lshl_add_u64 v[6:7], s[38:39], 0, v[184:185]
	v_lshl_add_u32 v41, v10, 2, s2
	v_lshlrev_b64 v[10:11], 12, v[0:1]
	v_ashrrev_i32_e32 v13, 31, v12
	v_add_u32_e32 v18, 32, v0
	v_add_u32_e32 v24, 48, v0
	v_lshlrev_b32_e32 v184, 2, v2
	v_mad_u32_u24 v1, v34, s90, v36
	s_add_u32 s22, s62, s22
	v_lshrrev_b32_e32 v34, 4, v35
	v_lshlrev_b32_e32 v8, 6, v0
	v_lshlrev_b32_e32 v14, 6, v12
	v_lshlrev_b64 v[16:17], 12, v[12:13]
	v_lshlrev_b32_e32 v20, 6, v18
	v_ashrrev_i32_e32 v19, 31, v18
	v_lshlrev_b32_e32 v26, 6, v24
	v_ashrrev_i32_e32 v25, 31, v24
	v_lshl_add_u64 v[30:31], s[0:1], 0, v[184:185]
	s_addc_u32 s23, s63, s23
	v_lshlrev_b32_e32 v13, 6, v34
	s_add_i32 s0, s2, 0x4100
	v_ashrrev_i32_e32 v9, 31, v8
	v_ashrrev_i32_e32 v15, 31, v14
	v_ashrrev_i32_e32 v21, 31, v20
	v_lshlrev_b64 v[22:23], 12, v[18:19]
	v_ashrrev_i32_e32 v27, 31, v26
	v_lshlrev_b64 v[28:29], 12, v[24:25]
	v_lshl_add_u64 v[32:33], s[26:27], 0, v[184:185]
	s_movk_i32 s33, 0x3fff
	v_add_u32_e32 v19, s0, v13
	v_lshlrev_b32_e32 v25, 5, v34
	v_mul_lo_u32 v42, v34, 48
	v_readlane_b32 s5, v253, 33
	v_readlane_b32 s6, v253, 34
	v_readlane_b32 s7, v253, 35
	v_readlane_b32 s8, v253, 36
	v_readlane_b32 s9, v253, 37
	v_readlane_b32 s10, v253, 38
	v_readlane_b32 s11, v253, 39
	v_readlane_b32 s12, v253, 40
	v_readlane_b32 s13, v253, 41
	v_readlane_b32 s14, v253, 42
	v_readlane_b32 s15, v253, 43
	v_readlane_b32 s16, v253, 44
	v_readlane_b32 s17, v253, 45
	s_branch .LBB0_153
